# MLP weight conversion split: w_up between arrive/wait of grid barrier 4, w_dn between arrive/wait of grid barrier 6; L1 invalidate by wave 1 at arrival
# speedup vs baseline: 1.0465x; 1.0196x over previous
; __device__ __forceinline__ unsigned xb_ld(unsigned* p)              { return __hip_atomic_load(p, __ATOMIC_RELAXED, __HIP_MEMORY_SCOPE_AGENT); }
; __device__ __forceinline__ void xcd_barrier_complete(unsigned* bar, unsigned x, unsigned& nloc, unsigned& nx) {
;     const unsigned G = gridDim.x * gridDim.y * gridDim.z;
;     unsigned sum, cnt, mine, sp = 0u;
;     for (;;) {
;         sum = 0u; cnt = 0u; mine = 0u;
; #pragma unroll
;         for (unsigned j = 0; j < 16; ++j) { const unsigned c = xb_ld(&bar[XB_XCNT(j)]); sum += c; cnt += (c > 0u) ? 1u : 0u; mine = (j == x) ? c : mine; }
;         if (sum == G) break;
;         __builtin_amdgcn_s_sleep(1);
;         if ((++sp & 255u) == 0u) { if (xb_ld(&bar[XB_TMO])) break; if (sp > XB_SPIN_CAP) { atomicAdd(&bar[XB_TMO], 1u); break; } }
;     }
;     nloc = mine > 0u ? mine : 1u; nx = cnt > 0u ? cnt : 1u;
; }
; __device__ __forceinline__ void xcd_barrier(const XcdBarrier& b) {
;     asm volatile("s_waitcnt vmcnt(0)" ::: "memory");
;     __syncthreads();
;     if (threadIdx.x == 0) {
;         unsigned* bar = b.bar;
;         __builtin_amdgcn_s_waitcnt(0);
;         unsigned nloc = b.st[0], nx = b.st[1];
;         if (nloc == 0u) { xcd_barrier_complete(bar, b.x, nloc, nx); b.st[0] = nloc; b.st[1] = nx; }
.LBB0_108:
	s_add_u32 s88, s92, 0xff40200
	s_addc_u32 s89, s93, 0
	s_add_u32 s14, s92, 0xff40400
	s_addc_u32 s15, s93, 0
	s_add_u32 s62, s92, 0xff40500
	s_addc_u32 s63, s93, 0
	s_add_u32 s36, s92, 0xff40600
	s_addc_u32 s37, s93, 0
	s_add_u32 s70, s92, 0xff40700
	s_mul_i32 s0, s95, s94
	s_addc_u32 s71, s93, 0
	s_mul_i32 s6, s0, s34
	s_add_u32 s34, s92, 0xff40800
	s_addc_u32 s35, s93, 0
	s_add_u32 s96, s92, 0xff40900
	s_addc_u32 s97, s93, 0
	s_add_u32 s56, s92, 0xff40a00
	s_addc_u32 s57, s93, 0
	s_add_u32 s0, s92, 0xff40b00
	s_addc_u32 s1, s93, 0
	v_writelane_b32 v241, s0, 26
	v_writelane_b32 v240, s18, 28
	s_waitcnt vmcnt(0)
	s_nop 0
	v_writelane_b32 v241, s1, 27
	s_add_u32 s0, s92, 0xff40c00
	s_addc_u32 s1, s93, 0
	v_writelane_b32 v241, s0, 28
	v_writelane_b32 v240, s19, 29
	s_barrier
	v_readfirstlane_b32 s100, v210
	s_nop 0
	s_lshr_b32 s100, s100, 6
	s_cmp_lg_u32 s100, 1
	s_cbranch_scc1 .Lbinv_1
	buffer_inv sc1
	s_waitcnt vmcnt(0)
.Lbinv_1:
	v_writelane_b32 v241, s1, 29
	s_add_u32 s0, s92, 0xff40d00
	s_addc_u32 s1, s93, 0
	v_writelane_b32 v241, s0, 30
	s_nop 1
	v_writelane_b32 v241, s1, 31
	s_add_u32 s0, s92, 0xff40e00
	s_addc_u32 s1, s93, 0
	v_writelane_b32 v241, s0, 32
	s_nop 1
	v_writelane_b32 v241, s1, 33
	s_add_u32 s0, s92, 0xff40f00
	s_addc_u32 s1, s93, 0
	v_writelane_b32 v241, s0, 34
	s_nop 1
	v_writelane_b32 v241, s1, 35
	s_add_u32 s0, s92, 0xff41000
	s_addc_u32 s1, s93, 0
	v_writelane_b32 v241, s0, 36
	s_nop 1
	v_writelane_b32 v241, s1, 37
	s_add_u32 s0, s92, 0xff41100
	s_addc_u32 s1, s93, 0
	v_writelane_b32 v241, s0, 38
	s_nop 1
	v_writelane_b32 v241, s1, 39
	s_add_u32 s0, s92, 0xff41200
	s_addc_u32 s1, s93, 0
	v_writelane_b32 v241, s0, 40
	s_nop 1
	v_writelane_b32 v241, s1, 41
	s_add_u32 s0, s92, 0xff41300
	s_addc_u32 s1, s93, 0
	v_writelane_b32 v241, s0, 42
	s_cmp_eq_u32 s3, 15
	s_nop 0
	v_writelane_b32 v241, s1, 43
	s_cselect_b64 s[0:1], -1, 0
	v_writelane_b32 v240, s0, 10
	s_cmp_eq_u32 s3, 14
	s_nop 0
	v_writelane_b32 v240, s1, 11
	s_cselect_b64 s[0:1], -1, 0
	v_writelane_b32 v240, s0, 8
	s_cmp_eq_u32 s3, 13
	s_nop 0
	v_writelane_b32 v240, s1, 9
	s_cselect_b64 s[0:1], -1, 0
	v_writelane_b32 v240, s0, 6
	s_cmp_eq_u32 s3, 12
	s_nop 0
	v_writelane_b32 v240, s1, 7
	s_cselect_b64 s[0:1], -1, 0
	v_writelane_b32 v240, s0, 4
	s_cmp_eq_u32 s3, 11
	s_nop 0
	v_writelane_b32 v240, s1, 5
	s_cselect_b64 s[0:1], -1, 0
	v_writelane_b32 v240, s0, 2
	s_cmp_eq_u32 s3, 10
	s_nop 0
	v_writelane_b32 v240, s1, 3
	s_cselect_b64 s[0:1], -1, 0
	v_writelane_b32 v240, s0, 0
	s_cmp_eq_u32 s3, 9
	s_nop 0
	v_writelane_b32 v240, s1, 1
	s_cselect_b64 s[0:1], -1, 0
	v_writelane_b32 v241, s0, 62
	s_cmp_eq_u32 s3, 8
	s_nop 0
	v_writelane_b32 v241, s1, 63
	s_cselect_b64 s[0:1], -1, 0
	v_writelane_b32 v241, s0, 60
	s_cmp_eq_u32 s3, 7
	s_nop 0
	v_writelane_b32 v241, s1, 61
	s_cselect_b64 s[0:1], -1, 0
	v_writelane_b32 v241, s0, 58
	s_cmp_eq_u32 s3, 6
	s_nop 0
	v_writelane_b32 v241, s1, 59
	s_cselect_b64 s[0:1], -1, 0
	v_writelane_b32 v241, s0, 56
	s_cmp_eq_u32 s3, 5
	s_nop 0
	v_writelane_b32 v241, s1, 57
	s_cselect_b64 s[0:1], -1, 0
	v_writelane_b32 v241, s0, 54
	s_cmp_eq_u32 s3, 4
	s_nop 0
	v_writelane_b32 v241, s1, 55
	s_cselect_b64 s[0:1], -1, 0
	v_writelane_b32 v241, s0, 52
	s_cmp_eq_u32 s3, 3
	s_nop 0
	v_writelane_b32 v241, s1, 53
	s_cselect_b64 s[0:1], -1, 0
	v_writelane_b32 v241, s0, 50
	s_cmp_eq_u32 s3, 2
	s_nop 0
	v_writelane_b32 v241, s1, 51
	s_cselect_b64 s[0:1], -1, 0
	v_writelane_b32 v241, s0, 48
	s_cmp_eq_u32 s3, 1
	s_nop 0
	v_writelane_b32 v241, s1, 49
	s_cselect_b64 s[0:1], -1, 0
	v_writelane_b32 v241, s0, 46
	s_cmp_eq_u32 s3, 0
	s_nop 0
	v_writelane_b32 v241, s1, 47
	s_cselect_b64 s[0:1], -1, 0
	v_writelane_b32 v241, s0, 44
	s_nop 1
	v_writelane_b32 v241, s1, 45
	s_lshl_b32 s0, s42, 2
	s_add_u32 s0, s38, s0
	s_addc_u32 s1, s39, 0
	s_add_u32 s4, s0, 0x1400
	s_addc_u32 s5, s1, 0
	v_writelane_b32 v240, s4, 12
	s_add_u32 s0, s0, 0x2400
	s_addc_u32 s1, s1, 0
	v_writelane_b32 v240, s5, 13
	v_writelane_b32 v240, s0, 14
	v_readlane_b32 s4, v241, 0
	v_readlane_b32 s5, v241, 1
	v_writelane_b32 v240, s1, 15
	s_add_u32 s0, s92, 0xff43400
	s_addc_u32 s1, s93, 0
	v_writelane_b32 v240, s0, 16
	s_nop 1
	v_writelane_b32 v240, s1, 17
	s_add_u32 s0, s92, 0xff43500
	s_addc_u32 s1, s93, 0
	v_writelane_b32 v240, s0, 18
	s_nop 1
	v_writelane_b32 v240, s1, 19
	s_and_saveexec_b64 s[0:1], s[4:5]
	s_cbranch_execz .LBB0_160
	s_add_i32 s3, 0, 0x23020
	v_mov_b32_e32 v0, s3
	s_waitcnt vmcnt(0) expcnt(0) lgkmcnt(0)
	ds_read_b32 v2, v0
	s_add_i32 s3, 0, 0x23024
	v_mov_b32_e32 v0, s3
	ds_read_b32 v0, v0
	s_waitcnt lgkmcnt(1)
	v_cmp_ne_u32_e32 vcc, 0, v2
	s_cbranch_vccnz .LBB0_124
	s_mov_b32 s3, 1
	v_mov_b32_e32 v16, 0
	s_branch .LBB0_112

; __device__ __forceinline__ unsigned xb_ld(unsigned* p)              { return __hip_atomic_load(p, __ATOMIC_RELAXED, __HIP_MEMORY_SCOPE_AGENT); }
; __device__ __forceinline__ unsigned xb_add(unsigned* p, unsigned v) { return __hip_atomic_fetch_add(p, v, __ATOMIC_RELAXED, __HIP_MEMORY_SCOPE_AGENT); }
; #define XB_SPIN(cond, bar) do { unsigned _sp = 0; while (cond) { __builtin_amdgcn_s_sleep(1); \
;     if ((++_sp & 255u) == 0u) { if (xb_ld(&(bar)[XB_TMO])) break; if (_sp > XB_SPIN_CAP) { atomicAdd(&(bar)[XB_TMO], 1u); break; } } } } while (0)
; __device__ __forceinline__ void xcd_barrier(const XcdBarrier& b) {
;     ...
;             __builtin_amdgcn_fence(__ATOMIC_RELEASE, "agent");
;             asm volatile("s_waitcnt vmcnt(0)" ::: "memory");
;             const unsigned og = xb_add(&bar[XB_TOP], 1u);
;             const unsigned tg = og / nx;
;             if (og + 1u == (tg + 1u) * nx) xb_add(&bar[XB_TOPGEN], 1u);
;             else XB_SPIN(xb_ld(&bar[XB_TOPGEN]) == tg, bar);
;             __builtin_amdgcn_fence(__ATOMIC_ACQUIRE, "agent");
;             xb_add(&bar[XB_XGEN(b.x)], 1u);
.LBB0_157:
	s_or_b64 exec, exec, s[16:17]
	s_mov_b64 s[16:17], exec
	v_mbcnt_lo_u32_b32 v0, s16, 0
	v_mbcnt_hi_u32_b32 v0, s17, v0
	v_cmp_eq_u32_e32 vcc, 0, v0
	s_waitcnt vmcnt(0)
	s_and_saveexec_b64 s[18:19], vcc
	s_cbranch_execz .LBB0_159
	s_bcnt1_i32_b64 s3, s[16:17]
	v_readlane_b32 s4, v240, 14
	v_mov_b32_e32 v0, 0
	v_mov_b32_e32 v1, s3
	v_readlane_b32 s5, v240, 15
	s_nop 4
	global_atomic_add v0, v1, s[4:5]

; __device__ __forceinline__ void xcd_barrier(const XcdBarrier& b) {
;     asm volatile("s_waitcnt vmcnt(0)" ::: "memory");
;     __syncthreads();
;     if (threadIdx.x == 0) {
;         unsigned* bar = b.bar;
;         __builtin_amdgcn_s_waitcnt(0);
;         unsigned nloc = b.st[0], nx = b.st[1];
;         if (nloc == 0u) { xcd_barrier_complete(bar, b.x, nloc, nx); b.st[0] = nloc; b.st[1] = nx; }
.LBB0_205:
	s_waitcnt vmcnt(0)
	v_readlane_b32 s0, v241, 0
	v_readlane_b32 s1, v241, 1
	s_waitcnt vmcnt(0) lgkmcnt(0)
	s_barrier
	v_readfirstlane_b32 s100, v210
	s_nop 0
	s_lshr_b32 s100, s100, 6
	s_cmp_lg_u32 s100, 1
	s_cbranch_scc1 .Lbinv_2
	buffer_inv sc1
	s_waitcnt vmcnt(0)
.Lbinv_2:
	s_and_saveexec_b64 s[16:17], s[0:1]
	s_cbranch_execz .LBB0_257
	s_add_i32 s3, 0, 0x23020
	v_mov_b32_e32 v0, s3
	s_waitcnt vmcnt(0) expcnt(0) lgkmcnt(0)
	ds_read_b32 v2, v0
	s_add_i32 s3, 0, 0x23024
	v_mov_b32_e32 v0, s3
	ds_read_b32 v0, v0
	s_waitcnt lgkmcnt(1)
	v_cmp_ne_u32_e32 vcc, 0, v2
	s_cbranch_vccnz .LBB0_221
	s_mov_b32 s3, 1
	v_mov_b32_e32 v16, 0
	s_branch .LBB0_209

; __device__ __forceinline__ unsigned xb_ld(unsigned* p)              { return __hip_atomic_load(p, __ATOMIC_RELAXED, __HIP_MEMORY_SCOPE_AGENT); }
; __device__ __forceinline__ unsigned xb_add(unsigned* p, unsigned v) { return __hip_atomic_fetch_add(p, v, __ATOMIC_RELAXED, __HIP_MEMORY_SCOPE_AGENT); }
; #define XB_SPIN(cond, bar) do { unsigned _sp = 0; while (cond) { __builtin_amdgcn_s_sleep(1); \
;     if ((++_sp & 255u) == 0u) { if (xb_ld(&(bar)[XB_TMO])) break; if (_sp > XB_SPIN_CAP) { atomicAdd(&(bar)[XB_TMO], 1u); break; } } } } while (0)
; __device__ __forceinline__ void xcd_barrier(const XcdBarrier& b) {
;     ...
;             __builtin_amdgcn_fence(__ATOMIC_RELEASE, "agent");
;             asm volatile("s_waitcnt vmcnt(0)" ::: "memory");
;             const unsigned og = xb_add(&bar[XB_TOP], 1u);
;             const unsigned tg = og / nx;
;             if (og + 1u == (tg + 1u) * nx) xb_add(&bar[XB_TOPGEN], 1u);
;             else XB_SPIN(xb_ld(&bar[XB_TOPGEN]) == tg, bar);
;             __builtin_amdgcn_fence(__ATOMIC_ACQUIRE, "agent");
;             xb_add(&bar[XB_XGEN(b.x)], 1u);
.LBB0_254:
	s_or_b64 exec, exec, s[18:19]
	s_mov_b64 s[18:19], exec
	v_mbcnt_lo_u32_b32 v0, s18, 0
	v_mbcnt_hi_u32_b32 v0, s19, v0
	v_cmp_eq_u32_e32 vcc, 0, v0
	s_waitcnt vmcnt(0)
	s_and_saveexec_b64 s[22:23], vcc
	s_cbranch_execz .LBB0_256
	s_bcnt1_i32_b64 s3, s[18:19]
	v_readlane_b32 s0, v240, 14
	v_mov_b32_e32 v0, 0
	v_mov_b32_e32 v1, s3
	v_readlane_b32 s1, v240, 15
	s_nop 4
	global_atomic_add v0, v1, s[0:1]

; __device__ __forceinline__ void xcd_barrier(const XcdBarrier& b) {
;     asm volatile("s_waitcnt vmcnt(0)" ::: "memory");
;     __syncthreads();
;     if (threadIdx.x == 0) {
;         unsigned* bar = b.bar;
;         __builtin_amdgcn_s_waitcnt(0);
;         unsigned nloc = b.st[0], nx = b.st[1];
;         if (nloc == 0u) { xcd_barrier_complete(bar, b.x, nloc, nx); b.st[0] = nloc; b.st[1] = nx; }
.LBB0_398:
	s_barrier
	s_waitcnt vmcnt(0)
	v_readlane_b32 s0, v241, 0
	v_readlane_b32 s1, v241, 1
	s_barrier
	v_readfirstlane_b32 s100, v210
	s_nop 0
	s_lshr_b32 s100, s100, 6
	s_cmp_lg_u32 s100, 1
	s_cbranch_scc1 .Lbinv_3
	buffer_inv sc1
	s_waitcnt vmcnt(0)
.Lbinv_3:
	s_and_saveexec_b64 s[20:21], s[0:1]
	s_cbranch_execz .LBB0_450
	s_add_i32 s24, 0, 0x23020
	v_mov_b32_e32 v0, s24
	s_waitcnt vmcnt(0) expcnt(0) lgkmcnt(0)
	ds_read_b32 v2, v0
	s_add_i32 s24, 0, 0x23024
	v_mov_b32_e32 v0, s24
	ds_read_b32 v0, v0
	s_waitcnt lgkmcnt(1)
	v_cmp_ne_u32_e32 vcc, 0, v2
	s_cbranch_vccnz .LBB0_414
	s_mov_b32 s26, 1
	v_mov_b32_e32 v16, 0
	s_branch .LBB0_402

; __device__ __forceinline__ unsigned xb_ld(unsigned* p)              { return __hip_atomic_load(p, __ATOMIC_RELAXED, __HIP_MEMORY_SCOPE_AGENT); }
; __device__ __forceinline__ unsigned xb_add(unsigned* p, unsigned v) { return __hip_atomic_fetch_add(p, v, __ATOMIC_RELAXED, __HIP_MEMORY_SCOPE_AGENT); }
; #define XB_SPIN(cond, bar) do { unsigned _sp = 0; while (cond) { __builtin_amdgcn_s_sleep(1); \
;     if ((++_sp & 255u) == 0u) { if (xb_ld(&(bar)[XB_TMO])) break; if (_sp > XB_SPIN_CAP) { atomicAdd(&(bar)[XB_TMO], 1u); break; } } } } while (0)
; __device__ __forceinline__ void xcd_barrier(const XcdBarrier& b) {
;     ...
;             __builtin_amdgcn_fence(__ATOMIC_RELEASE, "agent");
;             asm volatile("s_waitcnt vmcnt(0)" ::: "memory");
;             const unsigned og = xb_add(&bar[XB_TOP], 1u);
;             const unsigned tg = og / nx;
;             if (og + 1u == (tg + 1u) * nx) xb_add(&bar[XB_TOPGEN], 1u);
;             else XB_SPIN(xb_ld(&bar[XB_TOPGEN]) == tg, bar);
;             __builtin_amdgcn_fence(__ATOMIC_ACQUIRE, "agent");
;             xb_add(&bar[XB_XGEN(b.x)], 1u);
.LBB0_447:
	s_or_b64 exec, exec, s[24:25]
	s_mov_b64 s[24:25], exec
	v_mbcnt_lo_u32_b32 v0, s24, 0
	v_mbcnt_hi_u32_b32 v0, s25, v0
	v_cmp_eq_u32_e32 vcc, 0, v0
	s_waitcnt vmcnt(0)
	s_and_saveexec_b64 s[38:39], vcc
	s_cbranch_execz .LBB0_449
	s_bcnt1_i32_b64 s24, s[24:25]
	v_readlane_b32 s0, v240, 14
	v_mov_b32_e32 v0, 0
	v_mov_b32_e32 v1, s24
	v_readlane_b32 s1, v240, 15
	s_nop 4
	global_atomic_add v0, v1, s[0:1]

; __device__ __forceinline__ void xcd_barrier(const XcdBarrier& b) {
;     asm volatile("s_waitcnt vmcnt(0)" ::: "memory");
;     __syncthreads();
;     if (threadIdx.x == 0) {
;         unsigned* bar = b.bar;
;         __builtin_amdgcn_s_waitcnt(0);
;         unsigned nloc = b.st[0], nx = b.st[1];
;         if (nloc == 0u) { xcd_barrier_complete(bar, b.x, nloc, nx); b.st[0] = nloc; b.st[1] = nx; }
.LBB0_459:
	s_mov_b32 s99, 0
	s_barrier
	s_waitcnt vmcnt(0)
	v_readlane_b32 s0, v241, 0
	v_readlane_b32 s1, v241, 1
	s_barrier
	v_readfirstlane_b32 s100, v210
	s_nop 0
	s_lshr_b32 s100, s100, 6
	s_cmp_lg_u32 s100, 1
	s_cbranch_scc1 .Lbinv_4
	buffer_inv sc1
	s_waitcnt vmcnt(0)
.Lbinv_4:
	s_and_saveexec_b64 s[10:11], s[0:1]
	s_cbranch_execz .LBB0_511
	s_add_i32 s20, 0, 0x23020
	v_mov_b32_e32 v0, s20
	s_waitcnt vmcnt(0) expcnt(0) lgkmcnt(0)
	ds_read_b32 v2, v0
	s_add_i32 s20, 0, 0x23024
	v_mov_b32_e32 v0, s20
	ds_read_b32 v0, v0
	s_waitcnt lgkmcnt(1)
	v_cmp_ne_u32_e32 vcc, 0, v2
	s_cbranch_vccnz .LBB0_475
	s_mov_b32 s26, 1
	v_mov_b32_e32 v16, 0
	s_branch .LBB0_463

; __device__ __forceinline__ unsigned xb_ld(unsigned* p)              { return __hip_atomic_load(p, __ATOMIC_RELAXED, __HIP_MEMORY_SCOPE_AGENT); }
; __device__ __forceinline__ unsigned xb_add(unsigned* p, unsigned v) { return __hip_atomic_fetch_add(p, v, __ATOMIC_RELAXED, __HIP_MEMORY_SCOPE_AGENT); }
; #define XB_SPIN(cond, bar) do { unsigned _sp = 0; while (cond) { __builtin_amdgcn_s_sleep(1); \
;     if ((++_sp & 255u) == 0u) { if (xb_ld(&(bar)[XB_TMO])) break; if (_sp > XB_SPIN_CAP) { atomicAdd(&(bar)[XB_TMO], 1u); break; } } } } while (0)
; __device__ __forceinline__ void xcd_barrier(const XcdBarrier& b) {
;     ...
;         const unsigned old = xb_add(&bar[XB_XSUB(b.x)], 1u);
;         const unsigned gen = old / nloc;
;         if (old + 1u == (gen + 1u) * nloc) {
;             __builtin_amdgcn_fence(__ATOMIC_RELEASE, "agent");
;             asm volatile("s_waitcnt vmcnt(0)" ::: "memory");
;             const unsigned og = xb_add(&bar[XB_TOP], 1u);
;             const unsigned tg = og / nx;
;             if (og + 1u == (tg + 1u) * nx) xb_add(&bar[XB_TOPGEN], 1u);
;             else XB_SPIN(xb_ld(&bar[XB_TOPGEN]) == tg, bar);
;             __builtin_amdgcn_fence(__ATOMIC_ACQUIRE, "agent");
;             xb_add(&bar[XB_XGEN(b.x)], 1u);
;             asm volatile("s_waitcnt vmcnt(0)" ::: "memory");
;         } else {
;             XB_SPIN(xb_ld(&bar[XB_XGEN(b.x)]) == gen, bar);
.LBB0_477:
	s_or_b64 exec, exec, s[20:21]
	v_cvt_f32_u32_e32 v4, v2
	s_waitcnt vmcnt(0)
	v_readfirstlane_b32 s20, v3
	v_sub_u32_e32 v3, 0, v2
	v_rcp_iflag_f32_e32 v4, v4
	v_add_u32_e32 v5, s20, v1
	v_mul_f32_e32 v4, 0x4f7ffffe, v4
	v_cvt_u32_f32_e32 v4, v4
	v_mul_lo_u32 v1, v3, v4
	v_mul_hi_u32 v1, v4, v1
	v_add_u32_e32 v1, v4, v1
	v_mul_hi_u32 v1, v5, v1
	v_mul_lo_u32 v3, v1, v2
	v_sub_u32_e32 v3, v5, v3
	v_add_u32_e32 v4, 1, v1
	v_cmp_ge_u32_e32 vcc, v3, v2
	s_nop 1
	v_cndmask_b32_e32 v1, v1, v4, vcc
	v_sub_u32_e32 v4, v3, v2
	v_cndmask_b32_e32 v3, v3, v4, vcc
	v_add_u32_e32 v4, 1, v1
	v_cmp_ge_u32_e32 vcc, v3, v2
	v_add_u32_e32 v3, 1, v5
	s_nop 0
	v_cndmask_b32_e32 v1, v1, v4, vcc
	v_mul_lo_u32 v4, v2, v1
	v_add_u32_e32 v2, v4, v2
	v_cmp_ne_u32_e32 vcc, v3, v2
	s_and_saveexec_b64 s[20:21], vcc
	s_xor_b64 s[20:21], exec, s[20:21]
	s_cbranch_execz .LBB0_491
	v_readlane_b32 s0, v240, 14
	s_waitcnt lgkmcnt(0)
	v_mov_b32_e32 v0, 0
	v_readlane_b32 s1, v240, 15
	s_nop 4
	v_readfirstlane_b32 s98, v1
	s_mov_b32 s99, 1
	v_cmp_ne_u32_e32 vcc, v1, v1
	s_and_saveexec_b64 s[22:23], vcc
	s_cbranch_execz .LBB0_490
	s_mov_b32 s26, 1
	s_mov_b64 s[24:25], 0
	s_branch .LBB0_481

; __device__ __forceinline__ unsigned xb_ld(unsigned* p)              { return __hip_atomic_load(p, __ATOMIC_RELAXED, __HIP_MEMORY_SCOPE_AGENT); }
; __device__ __forceinline__ unsigned xb_add(unsigned* p, unsigned v) { return __hip_atomic_fetch_add(p, v, __ATOMIC_RELAXED, __HIP_MEMORY_SCOPE_AGENT); }
; #define XB_SPIN(cond, bar) do { unsigned _sp = 0; while (cond) { __builtin_amdgcn_s_sleep(1); \
;     if ((++_sp & 255u) == 0u) { if (xb_ld(&(bar)[XB_TMO])) break; if (_sp > XB_SPIN_CAP) { atomicAdd(&(bar)[XB_TMO], 1u); break; } } } } while (0)
; __device__ __forceinline__ void xcd_barrier(const XcdBarrier& b) {
;     ...
;             __builtin_amdgcn_fence(__ATOMIC_RELEASE, "agent");
;             asm volatile("s_waitcnt vmcnt(0)" ::: "memory");
;             const unsigned og = xb_add(&bar[XB_TOP], 1u);
;             const unsigned tg = og / nx;
;             if (og + 1u == (tg + 1u) * nx) xb_add(&bar[XB_TOPGEN], 1u);
;             else XB_SPIN(xb_ld(&bar[XB_TOPGEN]) == tg, bar);
;             __builtin_amdgcn_fence(__ATOMIC_ACQUIRE, "agent");
;             xb_add(&bar[XB_XGEN(b.x)], 1u);
.LBB0_508:
	s_or_b64 exec, exec, s[20:21]
	s_mov_b64 s[20:21], exec
	v_mbcnt_lo_u32_b32 v0, s20, 0
	v_mbcnt_hi_u32_b32 v0, s21, v0
	v_cmp_eq_u32_e32 vcc, 0, v0
	s_waitcnt vmcnt(0)
	s_and_saveexec_b64 s[22:23], vcc
	s_cbranch_execz .LBB0_510
	s_bcnt1_i32_b64 s20, s[20:21]
	v_readlane_b32 s0, v240, 14
	v_mov_b32_e32 v0, 0
	v_mov_b32_e32 v1, s20
	v_readlane_b32 s1, v240, 15
	s_nop 4
	global_atomic_add v0, v1, s[0:1]

; __device__ __forceinline__ int opaque_tid() { int t = threadIdx.x; asm volatile("" : "+v"(t)); return t; }
; #define LAS __attribute__((address_space(3)))
; __device__ __forceinline__ void p0b_mlp_weights(const Args& a, LAS unsigned char* lds) {
;     const int tid = opaque_tid(), lane = tid & 63, wave = tid >> 6;
;     LAS float* scr = (LAS float*)(lds + wave * 16640);
;     const int gw = blockIdx.x * NWAVES + wave, NGW = gridDim.x * NWAVES;
;     constexpr int I_UP = (D_ / 64) * (FF / 64), I_DN = (FF / 64) * (D_ / 64);
;     for (int it = gw; it < I_UP + I_DN; it += NGW) {
;         if (it < I_UP) transpose_item(a.w_up, D_, FF, (bf16*)(a.ws + WS_WUP), a.ln_mlp_g, scr, it, FF / 64, lane);
;         else transpose_item(a.w_dn, FF, D_, (bf16*)(a.ws + WS_WDN), nullptr, scr, it - I_UP, D_ / 64, lane);
; __global__ void __launch_bounds__(NTHREADS, 2) fwd_megakernel(Args a) {
;     ...
;         float mq = 0.f, mk = 0.f;
;         for (int i = 0; i < 96; ++i) { mq = fmaxf(mq, fabsf(a.q_norm_g[i])); mk = fmaxf(mk, fabsf(a.k_norm_g[i])); }
;         const float mb = fminf(96.f * mq * mk * 0.10206207261596577f * LOG2E, 80.f);
.LBB0_512:
	s_add_u32 s20, s72, s10
	s_addc_u32 s21, s73, s11
	global_load_dwordx4 v[2:5], v0, s[20:21] offset:32
	global_load_dwordx4 v[6:9], v0, s[20:21] offset:16
	global_load_dwordx4 v[10:13], v0, s[20:21]
	s_add_u32 s20, s74, s10
	s_addc_u32 s21, s75, s11
	global_load_dwordx4 v[14:17], v0, s[20:21]
	global_load_dwordx4 v[18:21], v0, s[20:21] offset:16
	global_load_dwordx4 v[22:25], v0, s[20:21] offset:32
	s_add_u32 s10, s10, 48
	s_addc_u32 s11, s11, 0
	s_cmpk_eq_i32 s10, 0x180
	s_waitcnt vmcnt(3)
	v_max3_f32 v1, v82, |v10|, |v11|
	v_max3_f32 v1, v1, |v12|, |v13|
	s_waitcnt vmcnt(2)
	v_max3_f32 v10, v83, |v14|, |v15|
	v_max3_f32 v1, v1, |v6|, |v7|
	v_max3_f32 v6, v10, |v16|, |v17|
	v_max3_f32 v1, v1, |v8|, |v9|
	s_waitcnt vmcnt(1)
	v_max3_f32 v6, v6, |v18|, |v19|
	v_max3_f32 v1, v1, |v2|, |v3|
	v_max3_f32 v2, v6, |v20|, |v21|
	v_max3_f32 v82, v1, |v4|, |v5|
	s_waitcnt vmcnt(0)
	v_max3_f32 v1, v2, |v22|, |v23|
	v_max3_f32 v83, v1, |v24|, |v25|
	s_cbranch_scc0 .LBB0_512
	s_add_u32 s10, s92, 0xf6a0000
	v_mov_b32_e32 v0, v210
	s_addc_u32 s11, s93, 0
	v_readlane_b32 s0, v241, 19
	v_ashrrev_i32_e32 v1, 6, v0
	s_add_u32 s50, s92, 0xeea0000
	v_add_u32_e32 v84, s0, v1
	s_movk_i32 s20, 0x400
	s_addc_u32 s51, s93, 0
	v_cmp_gt_i32_e32 vcc, s20, v84
	s_and_saveexec_b64 s[20:21], vcc
	v_readlane_b32 s64, v241, 2
	v_readlane_b32 s72, v241, 10
	v_readlane_b32 s73, v241, 11
	v_readlane_b32 s74, v241, 12
	v_readlane_b32 s75, v241, 13
	v_readlane_b32 s76, v241, 14
	v_readlane_b32 s77, v241, 15
	v_readlane_b32 s78, v241, 16
	v_readlane_b32 s79, v241, 17
	v_readlane_b32 s65, v241, 3
	v_readlane_b32 s66, v241, 4
	v_readlane_b32 s67, v241, 5
	v_readlane_b32 s68, v241, 6
	v_readlane_b32 s69, v241, 7
	v_readlane_b32 s70, v241, 8
	v_readlane_b32 s71, v241, 9
	s_cbranch_execz .LBB0_554
	s_movk_i32 s24, 0x4100
	v_mul_lo_u32 v2, v1, s24
	v_add_u32_e32 v3, 0, v2
	v_bfe_u32 v85, v0, 4, 2
	v_lshlrev_b32_e32 v2, 2, v0
	v_bfe_u32 v87, v0, 3, 3
	v_lshlrev_b32_e32 v0, 3, v0
	v_and_b32_e32 v6, 56, v0
	v_and_b32_e32 v86, 60, v2
	v_mul_u32_u24_e32 v0, 0x104, v6
	v_lshlrev_b32_e32 v7, 2, v87
	v_lshlrev_b32_e32 v2, 2, v86
	v_add3_u32 v88, v3, v0, v7
	v_mov_b32_e32 v0, 0
	v_readlane_b32 s0, v241, 18
	v_add_u32_e32 v4, v3, v2
	v_mul_u32_u24_e32 v5, 0x104, v85
	v_mov_b32_e32 v3, v0
	v_lshl_add_u32 v96, v1, 6, s0
	v_lshlrev_b32_e32 v1, 2, v1
	s_cmp_lg_u64 s[72:73], 0
	v_lshl_add_u64 v[68:69], s[76:77], 0, v[2:3]
	v_lshl_add_u64 v[70:71], s[74:75], 0, v[2:3]
	v_lshlrev_b32_e32 v2, 1, v6
	v_lshl_add_u32 v1, s2, 5, v1
	v_add_u32_e32 v98, v4, v5
	s_mov_b64 s[22:23], 0
	s_cselect_b64 s[42:43], -1, 0
	v_or_b32_e32 v89, 8, v87
	v_or_b32_e32 v90, 16, v87
	v_or_b32_e32 v91, 24, v87
	v_or_b32_e32 v92, 32, v87
	v_or_b32_e32 v93, 40, v87
	v_or_b32_e32 v94, 48, v87
	v_or_b32_e32 v95, 56, v87
	v_lshl_add_u64 v[72:73], s[10:11], 0, v[2:3]
	v_lshl_add_u64 v[74:75], s[50:51], 0, v[2:3]
	v_add_u32_e32 v97, 0x3f000, v1
	s_lshl_b32 s26, s94, 5
	v_add_u32_e32 v99, 0x410, v98
	v_add_u32_e32 v100, 0x418, v98
	v_add_u32_e32 v101, 0x820, v98
	v_add_u32_e32 v102, 0x828, v98
	v_add_u32_e32 v103, 0xc30, v98
	v_add_u32_e32 v104, 0xc38, v98
	v_add_u32_e32 v105, 0x1040, v98
	v_add_u32_e32 v106, 0x1048, v98
	v_add_u32_e32 v107, 0x1450, v98
	v_add_u32_e32 v108, 0x1458, v98
	v_add_u32_e32 v109, 0x1860, v98
	v_add_u32_e32 v110, 0x1868, v98
	v_add_u32_e32 v111, 0x1c70, v98
	v_add_u32_e32 v112, 0x1c78, v98
	v_add_u32_e32 v113, 0x2080, v98
	v_add_u32_e32 v114, 0x2088, v98
	v_add_u32_e32 v115, 0x2490, v98
	v_add_u32_e32 v116, 0x2498, v98
	v_add_u32_e32 v117, 0x28a0, v98
	v_add_u32_e32 v118, 0x28a8, v98
	v_add_u32_e32 v119, 0x2cb0, v98
	v_add_u32_e32 v120, 0x2cb8, v98
	v_add_u32_e32 v121, 0x30c0, v98
	v_add_u32_e32 v122, 0x30c8, v98
	v_add_u32_e32 v123, 0x34d0, v98
	s_branch .LBB0_517

; __device__ __forceinline__ void p0b_mlp_weights(const Args& a, LAS unsigned char* lds) {
;     ...
;     for (int it = gw; it < I_UP + I_DN; it += NGW) {
;         if (it < I_UP) transpose_item(a.w_up, D_, FF, (bf16*)(a.ws + WS_WUP), a.ln_mlp_g, scr, it, FF / 64, lane);
;         else transpose_item(a.w_dn, FF, D_, (bf16*)(a.ws + WS_WDN), nullptr, scr, it - I_UP, D_ / 64, lane);
.LBB0_516:
	s_or_b64 exec, exec, s[44:45]
	v_add_u32_e32 v84, s40, v84
	s_movk_i32 s24, 0x3ff
	v_cmp_lt_i32_e32 vcc, s24, v84
	v_add_u32_e32 v96, s33, v96
	s_or_b64 s[22:23], vcc, s[22:23]
	v_add_u32_e32 v97, s26, v97
	s_andn2_b64 exec, exec, s[22:23]
	s_cbranch_execz .LBB0_554

; __device__ __forceinline__ void xcd_barrier(const XcdBarrier& b) {
;     asm volatile("s_waitcnt vmcnt(0)" ::: "memory");
;     __syncthreads();
;     if (threadIdx.x == 0) {
;         unsigned* bar = b.bar;
;         __builtin_amdgcn_s_waitcnt(0);
;         unsigned nloc = b.st[0], nx = b.st[1];
;         if (nloc == 0u) { xcd_barrier_complete(bar, b.x, nloc, nx); b.st[0] = nloc; b.st[1] = nx; }
.LBB0_652:
	s_waitcnt vmcnt(0)
	v_readlane_b32 s4, v241, 0
	v_readlane_b32 s5, v241, 1
	s_waitcnt lgkmcnt(0)
	s_barrier
	v_readfirstlane_b32 s100, v210
	s_nop 0
	s_lshr_b32 s100, s100, 6
	s_cmp_lg_u32 s100, 1
	s_cbranch_scc1 .Lbinv_5
	buffer_inv sc1
	s_waitcnt vmcnt(0)
.Lbinv_5:
	s_and_saveexec_b64 s[0:1], s[4:5]
	s_cbranch_execz .LBB0_704
	s_add_i32 s18, 0, 0x23020
	v_mov_b32_e32 v0, s18
	s_waitcnt vmcnt(0) expcnt(0) lgkmcnt(0)
	ds_read_b32 v2, v0
	s_add_i32 s18, 0, 0x23024
	v_mov_b32_e32 v0, s18
	ds_read_b32 v0, v0
	s_waitcnt lgkmcnt(1)
	v_cmp_ne_u32_e32 vcc, 0, v2
	s_cbranch_vccnz .LBB0_668
	s_mov_b32 s24, 1
	v_mov_b32_e32 v16, 0
	s_branch .LBB0_656

; __device__ __forceinline__ unsigned xb_ld(unsigned* p)              { return __hip_atomic_load(p, __ATOMIC_RELAXED, __HIP_MEMORY_SCOPE_AGENT); }
; __device__ __forceinline__ unsigned xb_add(unsigned* p, unsigned v) { return __hip_atomic_fetch_add(p, v, __ATOMIC_RELAXED, __HIP_MEMORY_SCOPE_AGENT); }
; #define XB_SPIN(cond, bar) do { unsigned _sp = 0; while (cond) { __builtin_amdgcn_s_sleep(1); \
;     if ((++_sp & 255u) == 0u) { if (xb_ld(&(bar)[XB_TMO])) break; if (_sp > XB_SPIN_CAP) { atomicAdd(&(bar)[XB_TMO], 1u); break; } } } } while (0)
; __device__ __forceinline__ void xcd_barrier(const XcdBarrier& b) {
;     ...
;             __builtin_amdgcn_fence(__ATOMIC_RELEASE, "agent");
;             asm volatile("s_waitcnt vmcnt(0)" ::: "memory");
;             const unsigned og = xb_add(&bar[XB_TOP], 1u);
;             const unsigned tg = og / nx;
;             if (og + 1u == (tg + 1u) * nx) xb_add(&bar[XB_TOPGEN], 1u);
;             else XB_SPIN(xb_ld(&bar[XB_TOPGEN]) == tg, bar);
;             __builtin_amdgcn_fence(__ATOMIC_ACQUIRE, "agent");
;             xb_add(&bar[XB_XGEN(b.x)], 1u);
.LBB0_701:
	s_or_b64 exec, exec, s[18:19]
	s_mov_b64 s[18:19], exec
	v_mbcnt_lo_u32_b32 v0, s18, 0
	v_mbcnt_hi_u32_b32 v0, s19, v0
	v_cmp_eq_u32_e32 vcc, 0, v0
	s_waitcnt vmcnt(0)
	s_and_saveexec_b64 s[20:21], vcc
	s_cbranch_execz .LBB0_703
	s_bcnt1_i32_b64 s18, s[18:19]
	v_readlane_b32 s4, v240, 14
	v_mov_b32_e32 v0, 0
	v_mov_b32_e32 v1, s18
	v_readlane_b32 s5, v240, 15
	s_nop 4
	global_atomic_add v0, v1, s[4:5]

; __device__ __forceinline__ void xcd_barrier(const XcdBarrier& b) {
;     asm volatile("s_waitcnt vmcnt(0)" ::: "memory");
;     __syncthreads();
;     if (threadIdx.x == 0) {
;         unsigned* bar = b.bar;
;         __builtin_amdgcn_s_waitcnt(0);
;         unsigned nloc = b.st[0], nx = b.st[1];
;         if (nloc == 0u) { xcd_barrier_complete(bar, b.x, nloc, nx); b.st[0] = nloc; b.st[1] = nx; }
.Lbinv_6:
	s_mov_b32 s99, 0
	s_and_saveexec_b64 s[0:1], s[4:5]
	v_readlane_b32 s16, v241, 2
	v_readlane_b32 s30, v241, 16
	v_readlane_b32 s31, v241, 17
	s_mov_b64 s[54:55], s[30:31]
	v_readlane_b32 s17, v241, 3
	v_readlane_b32 s18, v241, 4
	v_readlane_b32 s19, v241, 5
	v_readlane_b32 s20, v241, 6
	v_readlane_b32 s21, v241, 7
	v_readlane_b32 s22, v241, 8
	v_readlane_b32 s23, v241, 9
	v_readlane_b32 s24, v241, 10
	v_readlane_b32 s25, v241, 11
	v_readlane_b32 s26, v241, 12
	v_readlane_b32 s27, v241, 13
	v_readlane_b32 s28, v241, 14
	v_readlane_b32 s29, v241, 15
	s_cbranch_execz .LBB0_817
	s_add_i32 s8, 0, 0x23020
	v_mov_b32_e32 v0, s8
	s_waitcnt vmcnt(0) expcnt(0) lgkmcnt(0)
	ds_read_b32 v2, v0
	s_add_i32 s8, 0, 0x23024
	v_mov_b32_e32 v0, s8
	ds_read_b32 v0, v0
	s_waitcnt lgkmcnt(1)
	v_cmp_ne_u32_e32 vcc, 0, v2
	s_cbranch_vccnz .LBB0_781
	s_mov_b32 s20, 1
	v_mov_b32_e32 v16, 0
	s_branch .LBB0_769

; __device__ __forceinline__ unsigned xb_ld(unsigned* p)              { return __hip_atomic_load(p, __ATOMIC_RELAXED, __HIP_MEMORY_SCOPE_AGENT); }
; __device__ __forceinline__ unsigned xb_add(unsigned* p, unsigned v) { return __hip_atomic_fetch_add(p, v, __ATOMIC_RELAXED, __HIP_MEMORY_SCOPE_AGENT); }
; #define XB_SPIN(cond, bar) do { unsigned _sp = 0; while (cond) { __builtin_amdgcn_s_sleep(1); \
;     if ((++_sp & 255u) == 0u) { if (xb_ld(&(bar)[XB_TMO])) break; if (_sp > XB_SPIN_CAP) { atomicAdd(&(bar)[XB_TMO], 1u); break; } } } } while (0)
; __device__ __forceinline__ void xcd_barrier(const XcdBarrier& b) {
;     ...
;         const unsigned old = xb_add(&bar[XB_XSUB(b.x)], 1u);
;         const unsigned gen = old / nloc;
;         if (old + 1u == (gen + 1u) * nloc) {
;             __builtin_amdgcn_fence(__ATOMIC_RELEASE, "agent");
;             asm volatile("s_waitcnt vmcnt(0)" ::: "memory");
;             const unsigned og = xb_add(&bar[XB_TOP], 1u);
;             const unsigned tg = og / nx;
;             if (og + 1u == (tg + 1u) * nx) xb_add(&bar[XB_TOPGEN], 1u);
;             else XB_SPIN(xb_ld(&bar[XB_TOPGEN]) == tg, bar);
;             __builtin_amdgcn_fence(__ATOMIC_ACQUIRE, "agent");
;             xb_add(&bar[XB_XGEN(b.x)], 1u);
;             asm volatile("s_waitcnt vmcnt(0)" ::: "memory");
;         } else {
;             XB_SPIN(xb_ld(&bar[XB_XGEN(b.x)]) == gen, bar);
.LBB0_783:
	s_or_b64 exec, exec, s[8:9]
	v_cvt_f32_u32_e32 v4, v2
	s_waitcnt vmcnt(0)
	v_readfirstlane_b32 s8, v3
	v_sub_u32_e32 v3, 0, v2
	v_rcp_iflag_f32_e32 v4, v4
	v_add_u32_e32 v5, s8, v1
	v_mul_f32_e32 v4, 0x4f7ffffe, v4
	v_cvt_u32_f32_e32 v4, v4
	v_mul_lo_u32 v1, v3, v4
	v_mul_hi_u32 v1, v4, v1
	v_add_u32_e32 v1, v4, v1
	v_mul_hi_u32 v1, v5, v1
	v_mul_lo_u32 v3, v1, v2
	v_sub_u32_e32 v3, v5, v3
	v_add_u32_e32 v4, 1, v1
	v_cmp_ge_u32_e32 vcc, v3, v2
	s_nop 1
	v_cndmask_b32_e32 v1, v1, v4, vcc
	v_sub_u32_e32 v4, v3, v2
	v_cndmask_b32_e32 v3, v3, v4, vcc
	v_add_u32_e32 v4, 1, v1
	v_cmp_ge_u32_e32 vcc, v3, v2
	v_add_u32_e32 v3, 1, v5
	s_nop 0
	v_cndmask_b32_e32 v1, v1, v4, vcc
	v_mul_lo_u32 v4, v2, v1
	v_add_u32_e32 v2, v4, v2
	v_cmp_ne_u32_e32 vcc, v3, v2
	s_and_saveexec_b64 s[8:9], vcc
	s_xor_b64 s[8:9], exec, s[8:9]
	s_cbranch_execz .LBB0_797
	v_readlane_b32 s4, v240, 14
	s_waitcnt lgkmcnt(0)
	v_mov_b32_e32 v0, 0
	v_readlane_b32 s5, v240, 15
	s_nop 4
	v_readfirstlane_b32 s98, v1
	s_mov_b32 s99, 1
	v_cmp_ne_u32_e32 vcc, v1, v1
	s_and_saveexec_b64 s[16:17], vcc
	s_cbranch_execz .LBB0_796
	s_mov_b32 s26, 1
	s_mov_b64 s[18:19], 0
	s_branch .LBB0_787

; __device__ __forceinline__ unsigned xb_ld(unsigned* p)              { return __hip_atomic_load(p, __ATOMIC_RELAXED, __HIP_MEMORY_SCOPE_AGENT); }
; __device__ __forceinline__ unsigned xb_add(unsigned* p, unsigned v) { return __hip_atomic_fetch_add(p, v, __ATOMIC_RELAXED, __HIP_MEMORY_SCOPE_AGENT); }
; #define XB_SPIN(cond, bar) do { unsigned _sp = 0; while (cond) { __builtin_amdgcn_s_sleep(1); \
;     if ((++_sp & 255u) == 0u) { if (xb_ld(&(bar)[XB_TMO])) break; if (_sp > XB_SPIN_CAP) { atomicAdd(&(bar)[XB_TMO], 1u); break; } } } } while (0)
; __device__ __forceinline__ void xcd_barrier(const XcdBarrier& b) {
;     ...
;             __builtin_amdgcn_fence(__ATOMIC_RELEASE, "agent");
;             asm volatile("s_waitcnt vmcnt(0)" ::: "memory");
;             const unsigned og = xb_add(&bar[XB_TOP], 1u);
;             const unsigned tg = og / nx;
;             if (og + 1u == (tg + 1u) * nx) xb_add(&bar[XB_TOPGEN], 1u);
;             else XB_SPIN(xb_ld(&bar[XB_TOPGEN]) == tg, bar);
;             __builtin_amdgcn_fence(__ATOMIC_ACQUIRE, "agent");
;             xb_add(&bar[XB_XGEN(b.x)], 1u);
.LBB0_814:
	s_or_b64 exec, exec, s[8:9]
	s_mov_b64 s[8:9], exec
	v_mbcnt_lo_u32_b32 v0, s8, 0
	v_mbcnt_hi_u32_b32 v0, s9, v0
	v_cmp_eq_u32_e32 vcc, 0, v0
	s_waitcnt vmcnt(0)
	s_and_saveexec_b64 s[16:17], vcc
	s_cbranch_execz .LBB0_816
	s_bcnt1_i32_b64 s8, s[8:9]
	v_readlane_b32 s4, v240, 14
	v_mov_b32_e32 v0, 0
	v_mov_b32_e32 v1, s8
	v_readlane_b32 s5, v240, 15
	s_nop 4
	global_atomic_add v0, v1, s[4:5]

; __device__ __forceinline__ int opaque_tid() { int t = threadIdx.x; asm volatile("" : "+v"(t)); return t; }
; #define LAS __attribute__((address_space(3)))
; __device__ __forceinline__ void p0b_mlp_weights(const Args& a, LAS unsigned char* lds) {
;     const int tid = opaque_tid(), lane = tid & 63, wave = tid >> 6;
;     LAS float* scr = (LAS float*)(lds + wave * 16640);
;     const int gw = blockIdx.x * NWAVES + wave, NGW = gridDim.x * NWAVES;
;     constexpr int I_UP = (D_ / 64) * (FF / 64), I_DN = (FF / 64) * (D_ / 64);
;     for (int it = gw; it < I_UP + I_DN; it += NGW) {
;         if (it < I_UP) transpose_item(a.w_up, D_, FF, (bf16*)(a.ws + WS_WUP), a.ln_mlp_g, scr, it, FF / 64, lane);
;         else transpose_item(a.w_dn, FF, D_, (bf16*)(a.ws + WS_WDN), nullptr, scr, it - I_UP, D_ / 64, lane);
.LBB0_817:
	s_or_b64 exec, exec, s[0:1]
	v_mov_b32_e32 v18, v210
	s_waitcnt lgkmcnt(0)
	s_barrier
	v_writelane_b32 v130, s0, 0
	v_writelane_b32 v130, s10, 1
	v_writelane_b32 v130, s11, 2
	v_writelane_b32 v130, s20, 3
	v_writelane_b32 v130, s21, 4
	v_writelane_b32 v130, s22, 5
	v_writelane_b32 v130, s23, 6
	v_writelane_b32 v130, s24, 7
	v_writelane_b32 v130, s25, 8
	v_writelane_b32 v130, s26, 9
	v_writelane_b32 v130, s42, 10
	v_writelane_b32 v130, s43, 11
	v_writelane_b32 v130, s44, 12
	v_writelane_b32 v130, s45, 13
	v_writelane_b32 v130, s50, 14
	v_writelane_b32 v130, s51, 15
	v_writelane_b32 v130, s64, 16
	v_writelane_b32 v130, s65, 17
	v_writelane_b32 v130, s66, 18
	v_writelane_b32 v130, s67, 19
	v_writelane_b32 v130, s68, 20
	v_writelane_b32 v130, s69, 21
	v_writelane_b32 v130, s70, 22
	v_writelane_b32 v130, s71, 23
	v_writelane_b32 v130, s72, 24
	v_writelane_b32 v130, s73, 25
	v_writelane_b32 v130, s74, 26
	v_writelane_b32 v130, s75, 27
	v_writelane_b32 v130, s76, 28
	v_writelane_b32 v130, s77, 29
	v_writelane_b32 v130, s78, 30
	v_writelane_b32 v130, s79, 31
	v_writelane_b32 v130, s33, 32
	v_writelane_b32 v130, s40, 33
	s_lshl_b32 s40, s94, 3
	s_lshl_b32 s33, s94, 9
	s_add_u32 s10, s92, 0xf6a0000
	v_mov_b32_e32 v0, v210
	s_addc_u32 s11, s93, 0
	v_readlane_b32 s0, v241, 19
	v_ashrrev_i32_e32 v1, 6, v0
	s_add_u32 s50, s92, 0xeea0000
	v_add_u32_e32 v84, s0, v1
	v_add_u32_e32 v84, 0x400, v84
	s_movk_i32 s20, 0x800
	s_addc_u32 s51, s93, 0
	v_cmp_gt_i32_e32 vcc, s20, v84
	s_and_saveexec_b64 s[20:21], vcc
	v_readlane_b32 s64, v241, 2
	v_readlane_b32 s72, v241, 10
	v_readlane_b32 s73, v241, 11
	v_readlane_b32 s74, v241, 12
	v_readlane_b32 s75, v241, 13
	v_readlane_b32 s76, v241, 14
	v_readlane_b32 s77, v241, 15
	v_readlane_b32 s78, v241, 16
	v_readlane_b32 s79, v241, 17
	v_readlane_b32 s65, v241, 3
	v_readlane_b32 s66, v241, 4
	v_readlane_b32 s67, v241, 5
	v_readlane_b32 s68, v241, 6
	v_readlane_b32 s69, v241, 7
	v_readlane_b32 s70, v241, 8
	v_readlane_b32 s71, v241, 9
	s_cbranch_execz .Lw2_554
	s_movk_i32 s24, 0x4100
	v_mul_lo_u32 v2, v1, s24
	v_add_u32_e32 v3, 0, v2
	v_bfe_u32 v85, v0, 4, 2
	v_lshlrev_b32_e32 v2, 2, v0
	v_bfe_u32 v87, v0, 3, 3
	v_lshlrev_b32_e32 v0, 3, v0
	v_and_b32_e32 v6, 56, v0
	v_and_b32_e32 v86, 60, v2
	v_mul_u32_u24_e32 v0, 0x104, v6
	v_lshlrev_b32_e32 v7, 2, v87
	v_lshlrev_b32_e32 v2, 2, v86
	v_add3_u32 v88, v3, v0, v7
	v_mov_b32_e32 v0, 0
	v_readlane_b32 s0, v241, 18
	v_add_u32_e32 v4, v3, v2
	v_mul_u32_u24_e32 v5, 0x104, v85
	v_mov_b32_e32 v3, v0
	v_lshl_add_u32 v96, v1, 6, s0
	v_add_u32_e32 v96, 0x10000, v96
	v_lshlrev_b32_e32 v1, 2, v1
	s_cmp_lg_u64 s[72:73], 0
	v_lshl_add_u64 v[68:69], s[76:77], 0, v[2:3]
	v_lshl_add_u64 v[70:71], s[74:75], 0, v[2:3]
	v_lshlrev_b32_e32 v2, 1, v6
	v_lshl_add_u32 v1, s2, 5, v1
	v_add_u32_e32 v98, v4, v5
	s_mov_b64 s[22:23], 0
	s_cselect_b64 s[42:43], -1, 0
	v_or_b32_e32 v89, 8, v87
	v_or_b32_e32 v90, 16, v87
	v_or_b32_e32 v91, 24, v87
	v_or_b32_e32 v92, 32, v87
	v_or_b32_e32 v93, 40, v87
	v_or_b32_e32 v94, 48, v87
	v_or_b32_e32 v95, 56, v87
	v_lshl_add_u64 v[72:73], s[10:11], 0, v[2:3]
	v_lshl_add_u64 v[74:75], s[50:51], 0, v[2:3]
	v_add_u32_e32 v97, 0x40000, v1
	s_lshl_b32 s26, s94, 5
	v_add_u32_e32 v99, 0x410, v98
	v_add_u32_e32 v100, 0x418, v98
	v_add_u32_e32 v101, 0x820, v98
	v_add_u32_e32 v102, 0x828, v98
	v_add_u32_e32 v103, 0xc30, v98
	v_add_u32_e32 v104, 0xc38, v98
	v_add_u32_e32 v105, 0x1040, v98
	v_add_u32_e32 v106, 0x1048, v98
	v_add_u32_e32 v107, 0x1450, v98
	v_add_u32_e32 v108, 0x1458, v98
	v_add_u32_e32 v109, 0x1860, v98
	v_add_u32_e32 v110, 0x1868, v98
	v_add_u32_e32 v111, 0x1c70, v98
	v_add_u32_e32 v112, 0x1c78, v98
	v_add_u32_e32 v113, 0x2080, v98
	v_add_u32_e32 v114, 0x2088, v98
	v_add_u32_e32 v115, 0x2490, v98
	v_add_u32_e32 v116, 0x2498, v98
	v_add_u32_e32 v117, 0x28a0, v98
	v_add_u32_e32 v118, 0x28a8, v98
	v_add_u32_e32 v119, 0x2cb0, v98
	v_add_u32_e32 v120, 0x2cb8, v98
	v_add_u32_e32 v121, 0x30c0, v98
	v_add_u32_e32 v122, 0x30c8, v98
	v_add_u32_e32 v123, 0x34d0, v98
	s_branch .Lw2_517

; __device__ __forceinline__ unsigned xb_ld(unsigned* p)              { return __hip_atomic_load(p, __ATOMIC_RELAXED, __HIP_MEMORY_SCOPE_AGENT); }
; #define XB_SPIN(cond, bar) do { unsigned _sp = 0; while (cond) { __builtin_amdgcn_s_sleep(1); \
;     if ((++_sp & 255u) == 0u) { if (xb_ld(&(bar)[XB_TMO])) break; if (_sp > XB_SPIN_CAP) { atomicAdd(&(bar)[XB_TMO], 1u); break; } } } } while (0)
; __device__ __forceinline__ void xcd_barrier(const XcdBarrier& b) {
;     ...
;             XB_SPIN(xb_ld(&bar[XB_XGEN(b.x)]) == gen, bar);
;             __builtin_amdgcn_fence(__ATOMIC_ACQUIRE, "agent");
;             asm volatile("s_waitcnt vmcnt(0)" ::: "memory");
.Lw2_554:
	s_or_b64 exec, exec, s[20:21]
	v_readlane_b32 s0, v130, 0
	v_readlane_b32 s10, v130, 1
	v_readlane_b32 s11, v130, 2
	v_readlane_b32 s20, v130, 3
	v_readlane_b32 s21, v130, 4
	v_readlane_b32 s22, v130, 5
	v_readlane_b32 s23, v130, 6
	v_readlane_b32 s24, v130, 7
	v_readlane_b32 s25, v130, 8
	v_readlane_b32 s26, v130, 9
	v_readlane_b32 s42, v130, 10
	v_readlane_b32 s43, v130, 11
	v_readlane_b32 s44, v130, 12
	v_readlane_b32 s45, v130, 13
	v_readlane_b32 s50, v130, 14
	v_readlane_b32 s51, v130, 15
	v_readlane_b32 s64, v130, 16
	v_readlane_b32 s65, v130, 17
	v_readlane_b32 s66, v130, 18
	v_readlane_b32 s67, v130, 19
	v_readlane_b32 s68, v130, 20
	v_readlane_b32 s69, v130, 21
	v_readlane_b32 s70, v130, 22
	v_readlane_b32 s71, v130, 23
	v_readlane_b32 s72, v130, 24
	v_readlane_b32 s73, v130, 25
	v_readlane_b32 s74, v130, 26
	v_readlane_b32 s75, v130, 27
	v_readlane_b32 s76, v130, 28
	v_readlane_b32 s77, v130, 29
	v_readlane_b32 s78, v130, 30
	v_readlane_b32 s79, v130, 31
	v_readlane_b32 s33, v130, 32
	v_readlane_b32 s40, v130, 33
	v_mov_b32_e32 v18, v210
	s_cmp_eq_u32 s99, 0
	s_cbranch_scc1 .Lgb6_done
	v_readlane_b32 s100, v240, 14
	v_readlane_b32 s101, v240, 15
	s_mov_b32 s99, 0
	s_nop 3

; template <class Epi, class Sched, bool ALIGN_EPI = false, bool SP2 = false>
; __device__ __forceinline__ void gemm_phase(PG8_LAS unsigned char* lds, const Gemm g, const Sched& S, const Epi& E) {
;     ...
;     Unit cur, nxt; int ui = 0;
;     if (!S.next(0, cur)) return;
; __device__ __forceinline__ void xcd_barrier(const XcdBarrier& b) {
;     ...
;     __syncthreads();
.Lgb6_done:
	v_mov_b32_e32 v18, v210
	s_waitcnt vmcnt(0) lgkmcnt(0)
	s_barrier
	s_movk_i32 s22, 0x400
	v_readfirstlane_b32 s24, v18
	s_cmpk_gt_i32 s2, 0x3ff
	s_cbranch_scc1 .LBB0_844
	v_readlane_b32 s0, v240, 23
	v_readlane_b32 s1, v240, 24
	s_and_b64 vcc, exec, s[0:1]
	s_cbranch_vccz .LBB0_820
	v_readlane_b32 s0, v240, 25
	s_lshl_b32 s18, s0, 7
	s_mov_b64 s[4:5], s[62:63]
	s_cbranch_execz .LBB0_821
	s_branch .LBB0_822

; __device__ __forceinline__ void xcd_barrier(const XcdBarrier& b) {
;     asm volatile("s_waitcnt vmcnt(0)" ::: "memory");
;     __syncthreads();
;     if (threadIdx.x == 0) {
;         unsigned* bar = b.bar;
;         __builtin_amdgcn_s_waitcnt(0);
;         unsigned nloc = b.st[0], nx = b.st[1];
;         if (nloc == 0u) { xcd_barrier_complete(bar, b.x, nloc, nx); b.st[0] = nloc; b.st[1] = nx; }
.Lbinv_7:
	s_and_saveexec_b64 s[0:1], s[4:5]
	v_readlane_b32 s22, v240, 18
	v_readlane_b32 s23, v240, 19
	s_cbranch_execz .LBB0_896
	s_add_i32 s8, 0, 0x23020
	v_mov_b32_e32 v0, s8
	s_waitcnt vmcnt(0) expcnt(0) lgkmcnt(0)
	ds_read_b32 v2, v0
	s_add_i32 s8, 0, 0x23024
	v_mov_b32_e32 v0, s8
	ds_read_b32 v0, v0
	s_waitcnt lgkmcnt(1)
	v_cmp_ne_u32_e32 vcc, 0, v2
	s_cbranch_vccnz .LBB0_860
	s_mov_b32 s18, 1
	v_mov_b32_e32 v16, 0
	s_branch .LBB0_848

; __device__ __forceinline__ unsigned xb_ld(unsigned* p)              { return __hip_atomic_load(p, __ATOMIC_RELAXED, __HIP_MEMORY_SCOPE_AGENT); }
; __device__ __forceinline__ unsigned xb_add(unsigned* p, unsigned v) { return __hip_atomic_fetch_add(p, v, __ATOMIC_RELAXED, __HIP_MEMORY_SCOPE_AGENT); }
; #define XB_SPIN(cond, bar) do { unsigned _sp = 0; while (cond) { __builtin_amdgcn_s_sleep(1); \
;     if ((++_sp & 255u) == 0u) { if (xb_ld(&(bar)[XB_TMO])) break; if (_sp > XB_SPIN_CAP) { atomicAdd(&(bar)[XB_TMO], 1u); break; } } } } while (0)
; __device__ __forceinline__ void xcd_barrier(const XcdBarrier& b) {
;     ...
;             __builtin_amdgcn_fence(__ATOMIC_RELEASE, "agent");
;             asm volatile("s_waitcnt vmcnt(0)" ::: "memory");
;             const unsigned og = xb_add(&bar[XB_TOP], 1u);
;             const unsigned tg = og / nx;
;             if (og + 1u == (tg + 1u) * nx) xb_add(&bar[XB_TOPGEN], 1u);
;             else XB_SPIN(xb_ld(&bar[XB_TOPGEN]) == tg, bar);
;             __builtin_amdgcn_fence(__ATOMIC_ACQUIRE, "agent");
;             xb_add(&bar[XB_XGEN(b.x)], 1u);
.LBB0_893:
	s_or_b64 exec, exec, s[4:5]
	s_mov_b64 s[4:5], exec
	v_mbcnt_lo_u32_b32 v0, s4, 0
	v_mbcnt_hi_u32_b32 v0, s5, v0
	v_cmp_eq_u32_e32 vcc, 0, v0
	s_waitcnt vmcnt(0)
	s_and_saveexec_b64 s[6:7], vcc
	s_cbranch_execz .LBB0_895
	s_bcnt1_i32_b64 s4, s[4:5]
	v_mov_b32_e32 v1, s4
	v_readlane_b32 s4, v240, 14
	v_mov_b32_e32 v0, 0
	v_readlane_b32 s5, v240, 15
	s_nop 4
	global_atomic_add v0, v1, s[4:5]
